# up phase start de-serialised: the first K-tile's 8 LDS-DMA loads (and their address math) are issued before the rstd-table build instead of after its barrier, so the cold DMA latency overlaps the buil
# baseline (speedup 1.0000x reference)
; #define PG8_STAGE(bufoff, gbase, voff) do { _Pragma("unroll") for (int _i = 0; _i < 2; ++_i) \
;         __builtin_amdgcn_global_load_lds((const unsigned*)((const char*)(gbase) + (voff)[_i]), (PG8_LAS unsigned*)(lds + (bufoff) + ldsw + _i * 8192), 16, 0, 0); } while (0)
; template <class Epi, class Sched, bool ALIGN_EPI = false, bool SP2 = false>
; __device__ __forceinline__ void gemm_phase(PG8_LAS unsigned char* lds, const Gemm g, const Sched& S, const Epi& E) {
;     ...
;     for (int i = 0; i < 2; ++i) { int R, C; stage_rc(tid * 16 + i * 8192, R, C); const int Rb = Epi::PERM ? ((R & ~31) + perm32(R & 31)) : R;
;         voffA[i] = (unsigned)(R * K + C) * 2u; voffB[i] = (unsigned)(Rb * K + C) * 2u; }
;     const size_t kstep = (size_t)(BK * 2);
;     const size_t hstep = (size_t)HALF * K * 2;
;     const size_t tstep = 2 * hstep;
;     const unsigned ldsw = (unsigned)wid * 1024u;
;     const int aoff = lds_byte(wr * 64 + fr, fq * 8), boff = lds_byte(wc * 32 + fr, fq * 8);
;     ...
;     Unit cur, nxt; int ui = 0;
;     if (!S.next(0, cur)) return;
;     f32x4 acc[2][2][4][2];
; #pragma unroll
;     for (int a = 0; a < 2; ++a)
; #pragma unroll
;         for (int b = 0; b < 2; ++b)
; #pragma unroll
;             for (int m = 0; m < 4; ++m)
; #pragma unroll
;                 for (int n = 0; n < 2; ++n) acc[a][b][m][n] = (f32x4){0.f, 0.f, 0.f, 0.f};
;     bf16x8 At[4][2], B0[2][2], B1[2][2];
;     const char* cA = (const char*)g.A + (size_t)cur.pm * tstep; const char* cB = (const char*)g.Bt + (size_t)cur.pn * tstep;
;     S.a_ready(cur);
;     if constexpr (SP2) {
;         PG8_STAGE(PG8_SB(0, 0), cB, voffB); PG8_STAGE(PG8_SB(0, 1), cB + hstep, voffB); PG8_STAGE(PG8_SA(0, 0), cA, voffA); PG8_STAGE(PG8_SA(0, 1), cA + hstep, voffA);
; __device__ __forceinline__ void build_rstd_table(LAS unsigned char* lds, const float* ssp, const pg8::StaticOrder& S, int tid) {
;     ...
;     for (int k = 0; k < 6; ++k) { pg8::Unit u; ok[k] = S.next((tid >> 8) + 2 * k, u);
;         if (ok[k]) { const f32x4* q = (const f32x4*)(ssp + (size_t)(u.pm * 256 + (tid & 255)) * 16);
; #pragma unroll
;             for (int j = 0; j < 4; ++j) p[k][j] = q[j]; } }
.LBB0_419:
	s_mov_b64 s[4:5], s[92:93]
	s_load_dwordx4 s[0:3], s[4:5], 0xc8
	s_waitcnt lgkmcnt(0)
	s_waitcnt lgkmcnt(0)
	s_add_u32 s20, s0, s2
	s_addc_u32 s21, s1, s3
	s_mov_b64 s[36:37], s[26:27]
	s_andn2_b64 vcc, exec, s[72:73]
	s_cbranch_vccnz .Lup_noP
	v_readfirstlane_b32 s2, v145
	v_mov_b32_e32 v0, v145
	s_nop 3
	s_waitcnt vmcnt(2)
	v_lshlrev_b32_e32 v4, 4, v0
	v_add_u32_e32 v2, 0x2000, v4
	v_ashrrev_i32_e32 v1, 31, v2
	v_lshrrev_b32_e32 v1, 22, v1
	v_add_u32_e32 v1, v2, v1
	v_ashrrev_i32_e32 v1, 10, v1
	v_mul_i32_i24_e32 v3, 0x400, v1
	v_sub_u32_e32 v2, v2, v3
	v_lshrrev_b32_e32 v3, 4, v2
	s_ashr_i32 s3, s2, 6
	v_bitop3_b32 v3, v3, v2, 32 bitop3:0x6c
	s_ashr_i32 s4, s2, 8
	s_lshl_b32 s22, s3, 10
	v_ashrrev_i32_e32 v2, 31, v3
	s_add_u32 s23, s20, 0x11600000
	v_lshrrev_b32_e32 v2, 26, v2
	s_mul_i32 s0, s76, 0xb00000
	s_addc_u32 s24, s21, 0
	v_add_u32_e32 v5, v3, v2
	v_lshlrev_b32_e32 v6, 3, v1
	s_add_u32 s0, s20, s0
	v_ashrrev_i32_e32 v2, 6, v5
	v_and_b32_e32 v6, -16, v6
	s_addc_u32 s1, s21, 0
	v_add_u32_e32 v6, v2, v6
	s_mov_b32 s56, s25
	s_add_u32 s25, s0, 0xc000000
	v_and_b32_e32 v7, 3, v2
	s_mov_b32 s0, 0x1fffe0
	s_waitcnt vmcnt(1)
	v_lshrrev_b32_e32 v8, 2, v6
	v_lshlrev_b32_e32 v9, 1, v6
	v_and_b32_e32 v5, 0xc0, v5
	v_and_or_b32 v7, v6, s0, v7
	v_and_b32_e32 v8, 4, v8
	v_and_b32_e32 v9, 24, v9
	v_sub_u32_e32 v3, v3, v5
	v_or3_b32 v7, v7, v8, v9
	v_lshlrev_b32_e32 v8, 5, v1
	v_ashrrev_i16_sdwa v3, v199, sext(v3) dst_sel:DWORD dst_unused:UNUSED_PAD src0_sel:DWORD src1_sel:BYTE_0
	v_and_b32_e32 v8, 32, v8
	v_bfe_i32 v3, v3, 0, 16
	v_add_lshl_u32 v5, v8, v3, 1
	v_lshl_add_u32 v128, v7, 11, v5
	v_lshl_add_u32 v130, v6, 11, v5
	v_bfe_i32 v5, v0, 27, 1
	v_lshrrev_b32_e32 v5, 22, v5
	v_add_u32_e32 v5, v4, v5
	v_and_b32_e32 v5, 0xfffffc00, v5
	v_sub_u32_e32 v4, v4, v5
	v_lshrrev_b32_e32 v5, 4, v4
	v_bitop3_b32 v6, v5, v4, 32 bitop3:0x6c
	v_ashrrev_i32_e32 v5, 31, v0
	v_lshrrev_b32_e32 v5, 26, v5
	v_ashrrev_i32_e32 v4, 31, v6
	v_add_u32_e32 v5, v0, v5
	v_lshrrev_b32_e32 v4, 26, v4
	v_ashrrev_i32_e32 v5, 6, v5
	v_add_u32_e32 v7, v6, v4
	v_lshlrev_b32_e32 v8, 3, v5
	v_ashrrev_i32_e32 v4, 6, v7
	v_and_b32_e32 v8, -16, v8
	v_add_u32_e32 v8, v4, v8
	v_and_b32_e32 v9, 3, v4
	v_lshrrev_b32_e32 v10, 2, v8
	v_lshlrev_b32_e32 v11, 1, v8
	v_and_b32_e32 v7, 0xc0, v7
	v_and_or_b32 v9, v8, s0, v9
	v_and_b32_e32 v10, 4, v10
	v_and_b32_e32 v11, 24, v11
	v_sub_u32_e32 v6, v6, v7
	s_addc_u32 s26, s1, 0
	v_or3_b32 v9, v9, v10, v11
	v_lshlrev_b32_e32 v10, 5, v5
	v_ashrrev_i16_sdwa v6, v199, sext(v6) dst_sel:DWORD dst_unused:UNUSED_PAD src0_sel:DWORD src1_sel:BYTE_0
	v_readlane_b32 s0, v252, 24
	v_and_b32_e32 v10, 32, v10
	v_bfe_i32 v6, v6, 0, 16
	v_readlane_b32 s1, v252, 25
	s_add_u32 s16, s25, s0
	v_add_lshl_u32 v7, v10, v6, 1
	s_addc_u32 s17, s26, s1
	s_add_i32 s27, s22, 0x10000
	s_add_i32 s28, s22, 0x12000
	v_lshl_add_u32 v132, v9, 11, v7
	s_mov_b32 m0, s27
	s_add_u32 s0, s16, 0x40000
	global_load_lds_dwordx4 v132, s[16:17]
	s_mov_b32 m0, s28
	s_addc_u32 s1, s17, 0
	s_add_i32 s29, s22, 0x14000
	global_load_lds_dwordx4 v128, s[16:17]
	s_mov_b32 m0, s29
	s_add_i32 s30, s22, 0x16000
	global_load_lds_dwordx4 v132, s[0:1]
	s_mov_b32 m0, s30
	v_lshl_add_u32 v134, v8, 11, v7
	global_load_lds_dwordx4 v128, s[0:1]
	v_readlane_b32 s0, v252, 22
	v_readlane_b32 s1, v252, 23
	s_add_u32 s14, s23, s0
	s_addc_u32 s15, s24, s1
	s_add_i32 s31, s22, 0x2000
	s_mov_b32 m0, s22
	s_add_u32 s0, s14, 0x40000
	global_load_lds_dwordx4 v134, s[14:15]
	s_mov_b32 m0, s31
	s_addc_u32 s1, s15, 0
	s_add_i32 s33, s22, 0x4000
	global_load_lds_dwordx4 v130, s[14:15]
	s_mov_b32 m0, s33
	s_add_i32 s34, s22, 0x6000
	global_load_lds_dwordx4 v134, s[0:1]
	s_mov_b32 m0, s34
	global_load_lds_dwordx4 v130, s[0:1]
	s_mov_b64 s[98:99], s[14:15]
	s_mov_b64 s[100:101], s[16:17]
	v_mov_b32_e32 v101, v1
	v_mov_b32_e32 v102, v2
	v_mov_b32_e32 v103, v3
	v_mov_b32_e32 v104, v4
	v_mov_b32_e32 v105, v5
	v_mov_b32_e32 v106, v6
	v_mov_b32_e32 v107, v7
	v_mov_b32_e32 v108, v8
	v_mov_b32_e32 v109, v9
	v_mov_b32_e32 v110, v10
	v_mov_b32_e32 v111, v11
.Lup_noP:
	v_mov_b32_e32 v96, v145
	v_mov_b64_e32 v[0:1], s[96:97]
	v_ashrrev_i32_e32 v80, 8, v96
	s_add_u32 s0, s20, 0x10e00000
	v_mad_i64_i32 v[2:3], s[2:3], v80, s69, v[0:1]
	v_and_b32_e32 v81, 0xff, v96
	s_addc_u32 s1, s21, 0
	v_cmp_gt_i64_e32 vcc, s[36:37], v[2:3]
	s_and_saveexec_b64 s[2:3], vcc
	s_cbranch_execz .LBB0_421
	v_ashrrev_i32_e32 v0, 31, v2
	v_lshrrev_b32_e32 v0, 29, v0
	v_add_u32_e32 v0, v2, v0
	v_ashrrev_i32_e32 v1, 3, v0
	v_and_b32_e32 v0, -8, v0
	v_sub_u32_e32 v0, v2, v0
	v_cmp_gt_i32_e64 s[8:9], 0, v0
	s_mov_b32 s4, 0x2e8ba2e9
	s_nop 0
	v_cndmask_b32_e64 v2, v200, v201, s[8:9]
	v_mul_lo_u32 v0, v0, v2
	v_add_u32_e32 v0, v0, v1
	v_mul_hi_i32 v1, v0, s4
	v_lshrrev_b32_e32 v2, 31, v1
	v_ashrrev_i32_e32 v1, 5, v1
	v_add_u32_e32 v1, v1, v2
	v_lshlrev_b32_e32 v2, 3, v1
	v_sub_u32_e32 v3, 0x80, v2
	v_min_i32_e32 v3, 8, v3
	s_waitcnt vmcnt(0)
	v_sub_u32_e32 v4, 0, v3
	v_max_i32_e32 v3, v3, v4
	v_cvt_f32_u32_e32 v4, v3
	s_movk_i32 s4, 0xb0
	v_mul_lo_u32 v1, v1, s4
	v_sub_u32_e32 v0, v0, v1
	v_rcp_iflag_f32_e32 v4, v4
	v_sub_u32_e32 v5, 0, v0
	v_ashrrev_i32_e32 v1, 31, v0
	v_max_i32_e32 v0, v0, v5
	v_mul_f32_e32 v4, 0x4f7ffffe, v4
	v_cvt_u32_f32_e32 v4, v4
	v_sub_u32_e32 v5, 0, v3
	v_mul_lo_u32 v5, v5, v4
	v_mul_hi_u32 v5, v4, v5
	v_add_u32_e32 v4, v4, v5
	v_mul_hi_u32 v4, v0, v4
	v_mul_lo_u32 v4, v4, v3
	v_sub_u32_e32 v0, v0, v4
	v_sub_u32_e32 v4, v0, v3
	v_cmp_ge_u32_e64 s[8:9], v0, v3
	s_nop 1
	v_cndmask_b32_e64 v0, v0, v4, s[8:9]
	v_sub_u32_e32 v4, v0, v3
	v_cmp_ge_u32_e64 s[8:9], v0, v3
	s_nop 1
	v_cndmask_b32_e64 v0, v0, v4, s[8:9]
	v_xor_b32_e32 v0, v0, v1
	v_sub_u32_e32 v0, v0, v1
	v_add_u32_e32 v0, v2, v0
	v_lshl_or_b32 v0, v0, 8, v81
	v_ashrrev_i32_e32 v1, 31, v0
	v_lshlrev_b64 v[0:1], 6, v[0:1]
	v_lshl_add_u64 v[12:13], s[0:1], 0, v[0:1]
	global_load_dwordx4 v[0:3], v[12:13], off offset:48
	global_load_dwordx4 v[4:7], v[12:13], off offset:32
	global_load_dwordx4 v[8:11], v[12:13], off offset:16
	s_nop 0
	global_load_dwordx4 v[12:15], v[12:13], off
;     __host__ __device__ bool next(int i, Unit& u) const {
;         const long L = (long)i * G + c; if (L >= nwg) return false;
;         int wgid = (int)L; { const int q = nwg / NXCD, r = nwg % NXCD, xcd = wgid % NXCD, off = wgid / NXCD; wgid = (xcd < r ? xcd * (q + 1) : r * (q + 1) + (xcd - r) * q) + off; }
;         const int nig = WGM * nN, gid = wgid / nig, fm = gid * WGM, gsz = (nM - fm) < WGM ? (nM - fm) : WGM;
;         u.pm = fm + ((wgid % nig) % gsz); u.pn = (wgid % nig) / gsz; return true;
; __device__ __forceinline__ void build_rstd_table(LAS unsigned char* lds, const float* ssp, const pg8::StaticOrder& S, int tid) {
;     ...
;     for (int k = 0; k < 6; ++k) { pg8::Unit u; ok[k] = S.next((tid >> 8) + 2 * k, u);
;         if (ok[k]) { const f32x4* q = (const f32x4*)(ssp + (size_t)(u.pm * 256 + (tid & 255)) * 16);
; #pragma unroll
;             for (int j = 0; j < 4; ++j) p[k][j] = q[j]; } }
.LBB0_421:
	s_or_b64 exec, exec, s[2:3]
	v_add_u32_e32 v18, 2, v80
	v_mov_b64_e32 v[16:17], s[96:97]
	v_mad_i64_i32 v[18:19], s[2:3], v18, s69, v[16:17]
	v_cmp_gt_i64_e64 s[8:9], s[36:37], v[18:19]
	s_and_saveexec_b64 s[2:3], s[8:9]
	s_cbranch_execz .LBB0_423
	v_ashrrev_i32_e32 v16, 31, v18
	v_lshrrev_b32_e32 v16, 29, v16
	v_add_u32_e32 v16, v18, v16
	v_ashrrev_i32_e32 v17, 3, v16
	v_and_b32_e32 v16, -8, v16
	v_sub_u32_e32 v16, v18, v16
	v_cmp_gt_i32_e64 s[10:11], 0, v16
	s_mov_b32 s4, 0x2e8ba2e9
	s_nop 0
	v_cndmask_b32_e64 v18, v200, v201, s[10:11]
	v_mul_lo_u32 v16, v16, v18
	v_add_u32_e32 v16, v16, v17
	v_mul_hi_i32 v17, v16, s4
	v_lshrrev_b32_e32 v18, 31, v17
	v_ashrrev_i32_e32 v17, 5, v17
	v_add_u32_e32 v17, v17, v18
	v_lshlrev_b32_e32 v18, 3, v17
	v_sub_u32_e32 v19, 0x80, v18
	v_min_i32_e32 v19, 8, v19
	s_waitcnt vmcnt(0)
	v_sub_u32_e32 v20, 0, v19
	v_max_i32_e32 v19, v19, v20
	v_cvt_f32_u32_e32 v20, v19
	s_movk_i32 s4, 0xb0
	v_mul_lo_u32 v17, v17, s4
	v_sub_u32_e32 v16, v16, v17
	v_rcp_iflag_f32_e32 v20, v20
	v_sub_u32_e32 v21, 0, v16
	v_ashrrev_i32_e32 v17, 31, v16
	v_max_i32_e32 v16, v16, v21
	v_mul_f32_e32 v20, 0x4f7ffffe, v20
	v_cvt_u32_f32_e32 v20, v20
	v_sub_u32_e32 v21, 0, v19
	v_mul_lo_u32 v21, v21, v20
	v_mul_hi_u32 v21, v20, v21
	v_add_u32_e32 v20, v20, v21
	v_mul_hi_u32 v20, v16, v20
	v_mul_lo_u32 v20, v20, v19
	v_sub_u32_e32 v16, v16, v20
	v_sub_u32_e32 v20, v16, v19
	v_cmp_ge_u32_e64 s[10:11], v16, v19
	s_nop 1
	v_cndmask_b32_e64 v16, v16, v20, s[10:11]
	v_sub_u32_e32 v20, v16, v19
	v_cmp_ge_u32_e64 s[10:11], v16, v19
	s_nop 1
	v_cndmask_b32_e64 v16, v16, v20, s[10:11]
	v_xor_b32_e32 v16, v16, v17
	v_sub_u32_e32 v16, v16, v17
	v_add_u32_e32 v16, v18, v16
	v_lshl_or_b32 v16, v16, 8, v81
	v_ashrrev_i32_e32 v17, 31, v16
	v_lshlrev_b64 v[16:17], 6, v[16:17]
	v_lshl_add_u64 v[28:29], s[0:1], 0, v[16:17]
	global_load_dwordx4 v[16:19], v[28:29], off offset:48
	global_load_dwordx4 v[20:23], v[28:29], off offset:32
	global_load_dwordx4 v[24:27], v[28:29], off offset:16
	s_nop 0
	global_load_dwordx4 v[28:31], v[28:29], off
.LBB0_423:
	s_or_b64 exec, exec, s[2:3]
	v_add_u32_e32 v34, 4, v80
	v_mov_b64_e32 v[32:33], s[96:97]
	v_mad_i64_i32 v[34:35], s[2:3], v34, s69, v[32:33]
	v_cmp_gt_i64_e64 s[10:11], s[36:37], v[34:35]
	s_and_saveexec_b64 s[2:3], s[10:11]
	s_cbranch_execz .LBB0_425
	v_ashrrev_i32_e32 v32, 31, v34
	v_lshrrev_b32_e32 v32, 29, v32
	v_add_u32_e32 v32, v34, v32
	v_ashrrev_i32_e32 v33, 3, v32
	v_and_b32_e32 v32, -8, v32
	v_sub_u32_e32 v32, v34, v32
	v_cmp_gt_i32_e64 s[12:13], 0, v32
	s_mov_b32 s4, 0x2e8ba2e9
	s_nop 0
	v_cndmask_b32_e64 v34, v200, v201, s[12:13]
	v_mul_lo_u32 v32, v32, v34
	v_add_u32_e32 v32, v32, v33
	v_mul_hi_i32 v33, v32, s4
	v_lshrrev_b32_e32 v34, 31, v33
	v_ashrrev_i32_e32 v33, 5, v33
	v_add_u32_e32 v33, v33, v34
	v_lshlrev_b32_e32 v34, 3, v33
	v_sub_u32_e32 v35, 0x80, v34
	v_min_i32_e32 v35, 8, v35
	s_waitcnt vmcnt(0)
	v_sub_u32_e32 v36, 0, v35
	v_max_i32_e32 v35, v35, v36
	v_cvt_f32_u32_e32 v36, v35
	s_movk_i32 s4, 0xb0
	v_mul_lo_u32 v33, v33, s4
	v_sub_u32_e32 v32, v32, v33
	v_rcp_iflag_f32_e32 v36, v36
	v_sub_u32_e32 v37, 0, v32
	v_ashrrev_i32_e32 v33, 31, v32
	v_max_i32_e32 v32, v32, v37
	v_mul_f32_e32 v36, 0x4f7ffffe, v36
	v_cvt_u32_f32_e32 v36, v36
	v_sub_u32_e32 v37, 0, v35
	v_mul_lo_u32 v37, v37, v36
	v_mul_hi_u32 v37, v36, v37
	v_add_u32_e32 v36, v36, v37
	v_mul_hi_u32 v36, v32, v36
	v_mul_lo_u32 v36, v36, v35
	v_sub_u32_e32 v32, v32, v36
	v_sub_u32_e32 v36, v32, v35
	v_cmp_ge_u32_e64 s[12:13], v32, v35
	s_nop 1
	v_cndmask_b32_e64 v32, v32, v36, s[12:13]
	v_sub_u32_e32 v36, v32, v35
	v_cmp_ge_u32_e64 s[12:13], v32, v35
	s_nop 1
	v_cndmask_b32_e64 v32, v32, v36, s[12:13]
	v_xor_b32_e32 v32, v32, v33
	v_sub_u32_e32 v32, v32, v33
	v_add_u32_e32 v32, v34, v32
	v_lshl_or_b32 v32, v32, 8, v81
	v_ashrrev_i32_e32 v33, 31, v32
	v_lshlrev_b64 v[32:33], 6, v[32:33]
	v_lshl_add_u64 v[44:45], s[0:1], 0, v[32:33]
	global_load_dwordx4 v[32:35], v[44:45], off offset:48
	global_load_dwordx4 v[36:39], v[44:45], off offset:32
	global_load_dwordx4 v[40:43], v[44:45], off offset:16
	s_nop 0
	global_load_dwordx4 v[44:47], v[44:45], off
.LBB0_425:
	s_or_b64 exec, exec, s[2:3]
	v_add_u32_e32 v50, 6, v80
	v_mov_b64_e32 v[48:49], s[96:97]
	v_mad_i64_i32 v[50:51], s[2:3], v50, s69, v[48:49]
	v_cmp_gt_i64_e64 s[12:13], s[36:37], v[50:51]
	s_and_saveexec_b64 s[2:3], s[12:13]
	s_cbranch_execz .LBB0_427
	v_ashrrev_i32_e32 v48, 31, v50
	v_lshrrev_b32_e32 v48, 29, v48
	v_add_u32_e32 v48, v50, v48
	v_ashrrev_i32_e32 v49, 3, v48
	v_and_b32_e32 v48, -8, v48
	v_sub_u32_e32 v48, v50, v48
	v_cmp_gt_i32_e64 s[14:15], 0, v48
	s_mov_b32 s4, 0x2e8ba2e9
	s_nop 0
	v_cndmask_b32_e64 v50, v200, v201, s[14:15]
	v_mul_lo_u32 v48, v48, v50
	v_add_u32_e32 v48, v48, v49
	v_mul_hi_i32 v49, v48, s4
	v_lshrrev_b32_e32 v50, 31, v49
	v_ashrrev_i32_e32 v49, 5, v49
	v_add_u32_e32 v49, v49, v50
	v_lshlrev_b32_e32 v50, 3, v49
	v_sub_u32_e32 v51, 0x80, v50
	v_min_i32_e32 v51, 8, v51
	s_waitcnt vmcnt(0)
	v_sub_u32_e32 v52, 0, v51
	v_max_i32_e32 v51, v51, v52
	v_cvt_f32_u32_e32 v52, v51
	s_movk_i32 s4, 0xb0
	v_mul_lo_u32 v49, v49, s4
	v_sub_u32_e32 v48, v48, v49
	v_rcp_iflag_f32_e32 v52, v52
	v_sub_u32_e32 v53, 0, v48
	v_ashrrev_i32_e32 v49, 31, v48
	v_max_i32_e32 v48, v48, v53
	v_mul_f32_e32 v52, 0x4f7ffffe, v52
	v_cvt_u32_f32_e32 v52, v52
	v_sub_u32_e32 v53, 0, v51
	v_mul_lo_u32 v53, v53, v52
	v_mul_hi_u32 v53, v52, v53
	v_add_u32_e32 v52, v52, v53
	v_mul_hi_u32 v52, v48, v52
	v_mul_lo_u32 v52, v52, v51
	v_sub_u32_e32 v48, v48, v52
	v_sub_u32_e32 v52, v48, v51
	v_cmp_ge_u32_e64 s[14:15], v48, v51
	s_nop 1
	v_cndmask_b32_e64 v48, v48, v52, s[14:15]
	v_sub_u32_e32 v52, v48, v51
	v_cmp_ge_u32_e64 s[14:15], v48, v51
	s_nop 1
	v_cndmask_b32_e64 v48, v48, v52, s[14:15]
	v_xor_b32_e32 v48, v48, v49
	v_sub_u32_e32 v48, v48, v49
	v_add_u32_e32 v48, v50, v48
	v_lshl_or_b32 v48, v48, 8, v81
	v_ashrrev_i32_e32 v49, 31, v48
	v_lshlrev_b64 v[48:49], 6, v[48:49]
	v_lshl_add_u64 v[60:61], s[0:1], 0, v[48:49]
	global_load_dwordx4 v[48:51], v[60:61], off offset:48
	global_load_dwordx4 v[52:55], v[60:61], off offset:32
	global_load_dwordx4 v[56:59], v[60:61], off offset:16
	s_nop 0
	global_load_dwordx4 v[60:63], v[60:61], off
;     __host__ __device__ bool next(int i, Unit& u) const {
;         const long L = (long)i * G + c; if (L >= nwg) return false;
;         int wgid = (int)L; { const int q = nwg / NXCD, r = nwg % NXCD, xcd = wgid % NXCD, off = wgid / NXCD; wgid = (xcd < r ? xcd * (q + 1) : r * (q + 1) + (xcd - r) * q) + off; }
;         const int nig = WGM * nN, gid = wgid / nig, fm = gid * WGM, gsz = (nM - fm) < WGM ? (nM - fm) : WGM;
;         u.pm = fm + ((wgid % nig) % gsz); u.pn = (wgid % nig) / gsz; return true;
; __device__ __forceinline__ void build_rstd_table(LAS unsigned char* lds, const float* ssp, const pg8::StaticOrder& S, int tid) {
;     ...
;     for (int k = 0; k < 6; ++k) { pg8::Unit u; ok[k] = S.next((tid >> 8) + 2 * k, u);
;         if (ok[k]) { const f32x4* q = (const f32x4*)(ssp + (size_t)(u.pm * 256 + (tid & 255)) * 16);
; #pragma unroll
;             for (int j = 0; j < 4; ++j) p[k][j] = q[j]; } }
.LBB0_427:
	s_or_b64 exec, exec, s[2:3]
	v_add_u32_e32 v66, 8, v80
	v_mov_b64_e32 v[64:65], s[96:97]
	v_mad_i64_i32 v[66:67], s[2:3], v66, s69, v[64:65]
	v_cmp_gt_i64_e64 s[14:15], s[36:37], v[66:67]
	s_and_saveexec_b64 s[2:3], s[14:15]
	s_cbranch_execz .LBB0_429
	v_ashrrev_i32_e32 v64, 31, v66
	v_lshrrev_b32_e32 v64, 29, v64
	v_add_u32_e32 v64, v66, v64
	v_ashrrev_i32_e32 v65, 3, v64
	v_and_b32_e32 v64, -8, v64
	v_sub_u32_e32 v64, v66, v64
	v_cmp_gt_i32_e64 s[16:17], 0, v64
	s_mov_b32 s4, 0x2e8ba2e9
	s_nop 0
	v_cndmask_b32_e64 v66, v200, v201, s[16:17]
	v_mul_lo_u32 v64, v64, v66
	v_add_u32_e32 v64, v64, v65
	v_mul_hi_i32 v65, v64, s4
	v_lshrrev_b32_e32 v66, 31, v65
	v_ashrrev_i32_e32 v65, 5, v65
	v_add_u32_e32 v65, v65, v66
	v_lshlrev_b32_e32 v66, 3, v65
	v_sub_u32_e32 v67, 0x80, v66
	v_min_i32_e32 v67, 8, v67
	s_waitcnt vmcnt(0)
	v_sub_u32_e32 v68, 0, v67
	v_max_i32_e32 v67, v67, v68
	v_cvt_f32_u32_e32 v68, v67
	s_movk_i32 s4, 0xb0
	v_mul_lo_u32 v65, v65, s4
	v_sub_u32_e32 v64, v64, v65
	v_rcp_iflag_f32_e32 v68, v68
	v_sub_u32_e32 v69, 0, v64
	v_ashrrev_i32_e32 v65, 31, v64
	v_max_i32_e32 v64, v64, v69
	v_mul_f32_e32 v68, 0x4f7ffffe, v68
	v_cvt_u32_f32_e32 v68, v68
	v_sub_u32_e32 v69, 0, v67
	v_mul_lo_u32 v69, v69, v68
	v_mul_hi_u32 v69, v68, v69
	v_add_u32_e32 v68, v68, v69
	v_mul_hi_u32 v68, v64, v68
	v_mul_lo_u32 v68, v68, v67
	v_sub_u32_e32 v64, v64, v68
	v_sub_u32_e32 v68, v64, v67
	v_cmp_ge_u32_e64 s[16:17], v64, v67
	s_nop 1
	v_cndmask_b32_e64 v64, v64, v68, s[16:17]
	v_sub_u32_e32 v68, v64, v67
	v_cmp_ge_u32_e64 s[16:17], v64, v67
	s_nop 1
	v_cndmask_b32_e64 v64, v64, v68, s[16:17]
	v_xor_b32_e32 v64, v64, v65
	v_sub_u32_e32 v64, v64, v65
	v_add_u32_e32 v64, v66, v64
	v_lshl_or_b32 v64, v64, 8, v81
	v_ashrrev_i32_e32 v65, 31, v64
	v_lshlrev_b64 v[64:65], 6, v[64:65]
	v_lshl_add_u64 v[76:77], s[0:1], 0, v[64:65]
	global_load_dwordx4 v[64:67], v[76:77], off offset:16
	global_load_dwordx4 v[72:75], v[76:77], off
	global_load_dwordx4 v[68:71], v[76:77], off offset:32
	s_nop 0
	global_load_dwordx4 v[76:79], v[76:77], off offset:48
.LBB0_429:
	s_or_b64 exec, exec, s[2:3]
	v_add_u32_e32 v80, 10, v80
	v_mov_b64_e32 v[82:83], s[96:97]
	v_mad_i64_i32 v[82:83], s[2:3], v80, s69, v[82:83]
	v_cmp_gt_i64_e64 s[16:17], s[36:37], v[82:83]
	s_and_saveexec_b64 s[2:3], s[16:17]
	s_cbranch_execz .LBB0_452
	v_ashrrev_i32_e32 v80, 31, v82
	v_lshrrev_b32_e32 v80, 29, v80
	v_add_u32_e32 v80, v82, v80
	v_ashrrev_i32_e32 v83, 3, v80
	v_and_b32_e32 v80, -8, v80
	v_sub_u32_e32 v80, v82, v80
	v_cmp_gt_i32_e64 s[18:19], 0, v80
	s_mov_b32 s4, 0x2e8ba2e9
	s_nop 0
	v_cndmask_b32_e64 v82, v200, v201, s[18:19]
	v_mul_lo_u32 v80, v80, v82
	v_add_u32_e32 v80, v80, v83
	v_mul_hi_i32 v82, v80, s4
	v_lshrrev_b32_e32 v83, 31, v82
	v_ashrrev_i32_e32 v82, 5, v82
	v_add_u32_e32 v82, v82, v83
	v_lshlrev_b32_e32 v83, 3, v82
	s_waitcnt vmcnt(0)
	v_sub_u32_e32 v84, 0x80, v83
	v_min_i32_e32 v84, 8, v84
	v_sub_u32_e32 v85, 0, v84
	v_max_i32_e32 v84, v84, v85
	v_cvt_f32_u32_e32 v85, v84
	s_movk_i32 s4, 0xb0
	v_mul_lo_u32 v82, v82, s4
	v_sub_u32_e32 v80, v80, v82
	v_rcp_iflag_f32_e32 v85, v85
	v_sub_u32_e32 v86, 0, v80
	v_ashrrev_i32_e32 v82, 31, v80
	v_max_i32_e32 v80, v80, v86
	v_mul_f32_e32 v85, 0x4f7ffffe, v85
	v_cvt_u32_f32_e32 v85, v85
	v_sub_u32_e32 v86, 0, v84
	v_mul_lo_u32 v86, v86, v85
	v_mul_hi_u32 v86, v85, v86
	v_add_u32_e32 v85, v85, v86
	v_mul_hi_u32 v85, v80, v85
	v_mul_lo_u32 v85, v85, v84
	v_sub_u32_e32 v80, v80, v85
	v_sub_u32_e32 v85, v80, v84
	v_cmp_ge_u32_e64 s[18:19], v80, v84
	s_nop 1
	v_cndmask_b32_e64 v80, v80, v85, s[18:19]
	v_sub_u32_e32 v85, v80, v84
	v_cmp_ge_u32_e64 s[18:19], v80, v84
	s_nop 1
	v_cndmask_b32_e64 v80, v80, v85, s[18:19]
	v_xor_b32_e32 v80, v80, v82
	v_sub_u32_e32 v80, v80, v82
	v_add_u32_e32 v80, v83, v80
	v_lshl_or_b32 v80, v80, 8, v81
	v_ashrrev_i32_e32 v81, 31, v80
	v_lshlrev_b64 v[80:81], 6, v[80:81]
	v_lshl_add_u64 v[92:93], s[0:1], 0, v[80:81]
	global_load_dwordx4 v[80:83], v[92:93], off
	global_load_dwordx4 v[84:87], v[92:93], off offset:16
	global_load_dwordx4 v[88:91], v[92:93], off offset:32
	s_nop 0
	global_load_dwordx4 v[92:95], v[92:93], off offset:48
	s_or_b64 exec, exec, s[2:3]
	s_and_saveexec_b64 s[0:1], vcc
	s_cbranch_execnz .LBB0_453

; #define PG8_STAGE(bufoff, gbase, voff) do { _Pragma("unroll") for (int _i = 0; _i < 2; ++_i) \
;         __builtin_amdgcn_global_load_lds((const unsigned*)((const char*)(gbase) + (voff)[_i]), (PG8_LAS unsigned*)(lds + (bufoff) + ldsw + _i * 8192), 16, 0, 0); } while (0)
; #define PG8_BAR __builtin_amdgcn_s_barrier()
; template <class Epi, class Sched, bool ALIGN_EPI = false, bool SP2 = false>
; __device__ __forceinline__ void gemm_phase(PG8_LAS unsigned char* lds, const Gemm g, const Sched& S, const Epi& E) {
;     ...
;         PG8_STAGE(PG8_SB(0, 0), cB, voffB); PG8_STAGE(PG8_SB(0, 1), cB + hstep, voffB); PG8_STAGE(PG8_SA(0, 0), cA, voffA); PG8_STAGE(PG8_SA(0, 1), cA + hstep, voffA);
;         if (wr == 1) PG8_BAR;
; __device__ __forceinline__ void build_rstd_table(LAS unsigned char* lds, const float* ssp, const pg8::StaticOrder& S, int tid) {
;     ...
;     __syncthreads();
.LBB0_437:
	s_or_b64 exec, exec, s[0:1]
	s_waitcnt vmcnt(0)
	v_mov_b32_e32 v0, v145
	s_waitcnt lgkmcnt(0)
	s_barrier
	s_andn2_b64 vcc, exec, s[72:73]
	v_readfirstlane_b32 s2, v0
	s_cbranch_vccnz .LBB0_459
	s_mov_b64 s[14:15], s[98:99]
	s_mov_b64 s[16:17], s[100:101]
	v_mov_b32_e32 v1, v101
	v_mov_b32_e32 v2, v102
	v_mov_b32_e32 v3, v103
	v_mov_b32_e32 v4, v104
	v_mov_b32_e32 v5, v105
	v_mov_b32_e32 v6, v106
	v_mov_b32_e32 v7, v107
	v_mov_b32_e32 v8, v108
	v_mov_b32_e32 v9, v109
	v_mov_b32_e32 v10, v110
	v_mov_b32_e32 v11, v111
	s_ashr_i32 s3, s2, 6
	s_ashr_i32 s4, s2, 8
	s_mov_b32 s57, s76
	s_cmp_eq_u32 s4, 1
	s_cselect_b64 s[0:1], -1, 0
	s_cmp_lg_u32 s4, 1
	s_cbranch_scc1 .LBB0_440
	s_barrier
